# in-proj epilogue output stores marked nt (streaming) in both in-proj code copies
# speedup vs baseline: 1.0139x; 1.0067x over previous
.LBB0_648:
	s_cmpk_lt_i32 s60, 0x80
	v_cmp_ne_u32_e32 vcc, 0, v144
	v_readlane_b32 s66, v252, 9
	s_cselect_b64 s[44:45], -1, 0
	v_lshlrev_b32_e32 v176, 1, v136
	v_readlane_b32 s67, v252, 10
	s_cbranch_vccz .LBB0_651
	s_lshl_b32 s0, s60, 8
	s_add_i32 s20, s60, 0x7fff80
	s_lshr_b32 s21, s60, 3
	s_and_b32 s22, s0, 0x700
	s_and_b64 s[0:1], s[44:45], exec
	s_cselect_b32 s0, s21, s20
	s_cselect_b32 s20, s22, 0x800
	s_lshl_b32 s1, s61, 8
	s_lshl_b32 s0, s0, 9
	s_add_i32 s0, s0, s1
	s_add_i32 s21, s0, 0xfffff400
	s_add_i32 s22, s0, 0xfffffc00
	v_readlane_b32 s0, v252, 32
	s_add_i32 s30, s21, s0
	s_add_i32 s0, s22, s0
	s_and_b32 s0, s0, 0xffffff80
	s_cmp_lt_i32 s61, 8
	s_cselect_b64 vcc, -1, 0
	v_or_b32_e32 v152, s0, v166
	s_and_b64 s[0:1], vcc, exec
	s_movk_i32 s0, 0x118
	s_cselect_b32 s0, s0, 0x120
	v_readlane_b32 s4, v253, 0
	v_readlane_b32 s5, v253, 1
	s_add_u32 s0, s4, s0
	s_addc_u32 s1, s5, 0
	s_load_dwordx2 s[0:1], s[0:1], 0x0
	v_or_b32_e32 v144, s30, v160
	v_cndmask_b32_e32 v144, v144, v152, vcc
	s_movk_i32 s4, 0x1200
	s_lshl_b32 s70, s20, 1
	s_waitcnt lgkmcnt(0)
	v_mov_b64_e32 v[148:149], s[0:1]
	v_mad_i64_i32 v[144:145], s[0:1], v144, s4, v[148:149]
	v_readlane_b32 s0, v252, 28
	v_lshl_add_u64 v[144:145], v[144:145], 0, s[70:71]
	s_lshl_b32 s42, s0, 1
	s_mov_b32 s43, s71
	v_lshl_add_u64 v[144:145], v[144:145], 0, s[42:43]
	v_lshl_add_u64 v[150:151], v[144:145], 0, v[176:177]
	v_cvt_pk_bf16_f32 v144, v124, v125
	v_cvt_pk_bf16_f32 v145, v126, v127
	v_cvt_pk_bf16_f32 v146, v120, v121
	v_cvt_pk_bf16_f32 v147, v122, v123
	global_store_dwordx4 v[150:151], v[144:147], off nt
	s_nop 1
	v_cvt_pk_bf16_f32 v144, v108, v109
	v_cvt_pk_bf16_f32 v145, v110, v111
	v_cvt_pk_bf16_f32 v146, v104, v105
	v_cvt_pk_bf16_f32 v147, v106, v107
	global_store_dwordx4 v[150:151], v[144:147], off offset:64 nt
	s_nop 1
	v_or_b32_e32 v144, 16, v152
	v_or_b32_e32 v145, s30, v163
	v_cndmask_b32_e32 v144, v145, v144, vcc
	v_mad_i64_i32 v[144:145], s[0:1], v144, s4, v[148:149]
	v_lshl_add_u64 v[144:145], v[144:145], 0, s[70:71]
	v_lshl_add_u64 v[144:145], v[144:145], 0, s[42:43]
	v_lshl_add_u64 v[150:151], v[144:145], 0, v[176:177]
	v_cvt_pk_bf16_f32 v144, v116, v117
	v_cvt_pk_bf16_f32 v145, v118, v119
	v_cvt_pk_bf16_f32 v146, v112, v113
	v_cvt_pk_bf16_f32 v147, v114, v115
	global_store_dwordx4 v[150:151], v[144:147], off nt
	s_nop 1
	v_cvt_pk_bf16_f32 v144, v92, v93
	v_cvt_pk_bf16_f32 v145, v94, v95
	v_cvt_pk_bf16_f32 v146, v88, v89
	v_cvt_pk_bf16_f32 v147, v90, v91
	global_store_dwordx4 v[150:151], v[144:147], off offset:64 nt
	s_nop 1
	v_or_b32_e32 v144, 32, v152
	v_or_b32_e32 v145, s30, v164
	v_cndmask_b32_e32 v144, v145, v144, vcc
	v_mad_i64_i32 v[144:145], s[0:1], v144, s4, v[148:149]
	v_lshl_add_u64 v[144:145], v[144:145], 0, s[70:71]
	v_lshl_add_u64 v[144:145], v[144:145], 0, s[42:43]
	v_lshl_add_u64 v[150:151], v[144:145], 0, v[176:177]
	v_cvt_pk_bf16_f32 v144, v100, v101
	v_cvt_pk_bf16_f32 v145, v102, v103
	v_cvt_pk_bf16_f32 v146, v96, v97
	v_cvt_pk_bf16_f32 v147, v98, v99
	global_store_dwordx4 v[150:151], v[144:147], off nt
	s_nop 1
	v_cvt_pk_bf16_f32 v144, v76, v77
	v_cvt_pk_bf16_f32 v145, v78, v79
	v_cvt_pk_bf16_f32 v146, v72, v73
	v_cvt_pk_bf16_f32 v147, v74, v75
	global_store_dwordx4 v[150:151], v[144:147], off offset:64 nt
	s_nop 1
	v_or_b32_e32 v144, 48, v152
	v_or_b32_e32 v145, s30, v165
	v_cndmask_b32_e32 v144, v145, v144, vcc
	v_mad_i64_i32 v[144:145], s[0:1], v144, s4, v[148:149]
	v_lshl_add_u64 v[144:145], v[144:145], 0, s[70:71]
	v_lshl_add_u64 v[144:145], v[144:145], 0, s[42:43]
	v_readlane_b32 s0, v252, 30
	v_lshl_add_u64 v[150:151], v[144:145], 0, v[176:177]
	v_cvt_pk_bf16_f32 v144, v84, v85
	v_cvt_pk_bf16_f32 v145, v86, v87
	v_cvt_pk_bf16_f32 v146, v80, v81
	v_cvt_pk_bf16_f32 v147, v82, v83
	s_add_i32 s22, s22, s0
	global_store_dwordx4 v[150:151], v[144:147], off nt
	s_add_i32 s21, s21, s0
	s_and_b32 s0, s22, 0xffffff80
	v_cvt_pk_bf16_f32 v144, v68, v69
	v_cvt_pk_bf16_f32 v145, v70, v71
	v_cvt_pk_bf16_f32 v146, v64, v65
	v_cvt_pk_bf16_f32 v147, v66, v67
	global_store_dwordx4 v[150:151], v[144:147], off offset:64 nt
	v_or_b32_e32 v152, s0, v167
	s_nop 0
	v_or_b32_e32 v144, s21, v160
	v_cndmask_b32_e32 v144, v144, v152, vcc
	v_mad_i64_i32 v[144:145], s[0:1], v144, s4, v[148:149]
	v_lshl_add_u64 v[144:145], v[144:145], 0, s[70:71]
	v_lshl_add_u64 v[144:145], v[144:145], 0, s[42:43]
	v_lshl_add_u64 v[150:151], v[144:145], 0, v[176:177]
	v_cvt_pk_bf16_f32 v144, v60, v61
	v_cvt_pk_bf16_f32 v145, v62, v63
	v_cvt_pk_bf16_f32 v146, v56, v57
	v_cvt_pk_bf16_f32 v147, v58, v59
	global_store_dwordx4 v[150:151], v[144:147], off nt
	s_nop 1
	v_cvt_pk_bf16_f32 v144, v44, v45
	v_cvt_pk_bf16_f32 v145, v46, v47
	v_cvt_pk_bf16_f32 v146, v40, v41
	v_cvt_pk_bf16_f32 v147, v42, v43
	global_store_dwordx4 v[150:151], v[144:147], off offset:64 nt
	s_nop 1
	v_or_b32_e32 v144, 16, v152
	v_or_b32_e32 v145, s21, v163
	v_cndmask_b32_e32 v144, v145, v144, vcc
	v_mad_i64_i32 v[144:145], s[0:1], v144, s4, v[148:149]
	v_lshl_add_u64 v[144:145], v[144:145], 0, s[70:71]
	v_lshl_add_u64 v[144:145], v[144:145], 0, s[42:43]
	v_lshl_add_u64 v[150:151], v[144:145], 0, v[176:177]
	v_cvt_pk_bf16_f32 v144, v52, v53
	v_cvt_pk_bf16_f32 v145, v54, v55
	v_cvt_pk_bf16_f32 v146, v48, v49
	v_cvt_pk_bf16_f32 v147, v50, v51
	global_store_dwordx4 v[150:151], v[144:147], off nt
	s_nop 1
	v_cvt_pk_bf16_f32 v144, v28, v29
	v_cvt_pk_bf16_f32 v145, v30, v31
	v_cvt_pk_bf16_f32 v146, v24, v25
	v_cvt_pk_bf16_f32 v147, v26, v27
	global_store_dwordx4 v[150:151], v[144:147], off offset:64 nt
	s_nop 1
	v_or_b32_e32 v144, 32, v152
	v_or_b32_e32 v145, s21, v164
	v_cndmask_b32_e32 v144, v145, v144, vcc
	v_mad_i64_i32 v[144:145], s[0:1], v144, s4, v[148:149]
	v_lshl_add_u64 v[144:145], v[144:145], 0, s[70:71]
	v_lshl_add_u64 v[144:145], v[144:145], 0, s[42:43]
	v_lshl_add_u64 v[150:151], v[144:145], 0, v[176:177]
	v_cvt_pk_bf16_f32 v144, v36, v37
	v_cvt_pk_bf16_f32 v145, v38, v39
	v_cvt_pk_bf16_f32 v146, v32, v33
	v_cvt_pk_bf16_f32 v147, v34, v35
	global_store_dwordx4 v[150:151], v[144:147], off nt
	s_nop 1
	v_cvt_pk_bf16_f32 v144, v12, v13
	v_cvt_pk_bf16_f32 v145, v14, v15
	v_cvt_pk_bf16_f32 v146, v8, v9
	v_cvt_pk_bf16_f32 v147, v10, v11
	global_store_dwordx4 v[150:151], v[144:147], off offset:64 nt
	s_nop 1
	v_or_b32_e32 v144, 48, v152
	v_or_b32_e32 v145, s21, v165
	v_cndmask_b32_e32 v144, v145, v144, vcc
	v_mad_i64_i32 v[144:145], s[0:1], v144, s4, v[148:149]
	v_lshl_add_u64 v[144:145], v[144:145], 0, s[70:71]
	v_lshl_add_u64 v[144:145], v[144:145], 0, s[42:43]
	v_lshl_add_u64 v[148:149], v[144:145], 0, v[176:177]
	v_cvt_pk_bf16_f32 v144, v20, v21
	v_cvt_pk_bf16_f32 v145, v22, v23
	v_cvt_pk_bf16_f32 v146, v16, v17
	v_cvt_pk_bf16_f32 v147, v18, v19
	global_store_dwordx4 v[148:149], v[144:147], off nt
	s_nop 1
	v_cvt_pk_bf16_f32 v144, v4, v5
	v_cvt_pk_bf16_f32 v145, v6, v7
	v_cvt_pk_bf16_f32 v146, v0, v1
	v_cvt_pk_bf16_f32 v147, v2, v3
	global_store_dwordx4 v[148:149], v[144:147], off offset:64 nt
	s_cbranch_execz .LBB0_652
	s_andn2_b64 vcc, exec, s[58:59]
	s_mov_b64 s[0:1], -1
	s_cbranch_vccnz .LBB0_622
	s_branch .LBB0_670

.LBB0_669:
	s_lshl_b32 s20, s61, 8
	s_cmp_lt_u32 s61, 12
	s_movk_i32 s0, 0xfe00
	s_cselect_b32 s21, s0, 0xfffffc00
	s_and_b64 s[0:1], s[62:63], exec
	s_cselect_b32 s0, 0, s21
	s_ashr_i32 s61, s60, 31
	s_add_i32 s0, s0, s20
	s_lshl_b64 s[20:21], s[60:61], 8
	v_lshl_add_u64 v[144:145], v[138:139], 0, s[20:21]
	v_readlane_b32 s20, v253, 0
	v_readlane_b32 s21, v253, 1
	s_mov_b32 s30, s7
	s_mov_b32 s22, s6
	s_load_dwordx16 s[4:19], s[20:21], 0xf0
	v_cvt_pk_bf16_f32 v124, v124, v125
	v_cvt_pk_bf16_f32 v125, v126, v127
	v_cvt_pk_bf16_f32 v126, v120, v121
	s_waitcnt lgkmcnt(0)
	s_movk_i32 s4, 0x3c00
	v_mov_b64_e32 v[120:121], s[12:13]
	v_mad_u64_u32 v[120:121], s[20:21], v144, s4, v[120:121]
	v_cvt_pk_bf16_f32 v127, v122, v123
	v_mov_b32_e32 v122, v121
	v_mad_u64_u32 v[122:123], s[20:21], v145, s4, v[122:123]
	s_ashr_i32 s1, s0, 31
	v_mov_b32_e32 v121, v122
	v_lshl_add_u64 v[120:121], s[0:1], 1, v[120:121]
	v_readlane_b32 s0, v252, 28
	s_lshl_b32 s70, s0, 1
	v_lshl_add_u64 v[120:121], v[120:121], 0, s[70:71]
	v_lshl_add_u64 v[120:121], v[120:121], 0, v[176:177]
	v_cvt_pk_bf16_f32 v108, v108, v109
	v_cvt_pk_bf16_f32 v109, v110, v111
	v_cvt_pk_bf16_f32 v110, v104, v105
	v_cvt_pk_bf16_f32 v111, v106, v107
	s_mov_b64 s[0:1], 0x3c000
	global_store_dwordx4 v[120:121], v[108:111], off offset:64 nt
	v_cvt_pk_bf16_f32 v92, v92, v93
	v_cvt_pk_bf16_f32 v93, v94, v95
	v_lshl_add_u64 v[108:109], v[120:121], 0, s[0:1]
	s_mov_b32 s0, 0x3c000
	v_add_co_u32_e32 v110, vcc, s0, v120
	v_cvt_pk_bf16_f32 v94, v88, v89
	v_cvt_pk_bf16_f32 v95, v90, v91
	s_mov_b64 s[0:1], 0x78000
	v_addc_co_u32_e32 v111, vcc, 0, v121, vcc
	global_store_dwordx4 v[108:109], v[92:95], off offset:64 nt
	v_cvt_pk_bf16_f32 v76, v76, v77
	v_cvt_pk_bf16_f32 v77, v78, v79
	v_lshl_add_u64 v[92:93], v[120:121], 0, s[0:1]
	s_mov_b32 s0, 0x78000
	v_add_co_u32_e32 v94, vcc, s0, v120
	v_cvt_pk_bf16_f32 v78, v72, v73
	v_cvt_pk_bf16_f32 v79, v74, v75
	s_mov_b64 s[0:1], 0xb4000
	v_addc_co_u32_e32 v95, vcc, 0, v121, vcc
	global_store_dwordx4 v[92:93], v[76:79], off offset:64 nt
	v_cvt_pk_bf16_f32 v60, v60, v61
	v_cvt_pk_bf16_f32 v61, v62, v63
	v_lshl_add_u64 v[76:77], v[120:121], 0, s[0:1]
	s_mov_b32 s0, 0xb4000
	v_add_co_u32_e32 v78, vcc, s0, v120
	s_mov_b64 s[0:1], 0x1e0000
	s_nop 0
	v_addc_co_u32_e32 v79, vcc, 0, v121, vcc
	v_cvt_pk_bf16_f32 v62, v56, v57
	v_lshl_add_u64 v[56:57], v[120:121], 0, s[0:1]
	s_mov_b32 s0, 0x1e0000
	v_cvt_pk_bf16_f32 v63, v58, v59
	v_add_co_u32_e32 v58, vcc, s0, v120
	v_cvt_pk_bf16_f32 v44, v44, v45
	v_cvt_pk_bf16_f32 v45, v46, v47
	v_cvt_pk_bf16_f32 v46, v40, v41
	v_cvt_pk_bf16_f32 v47, v42, v43
	s_mov_b64 s[0:1], 0x21c000
	v_addc_co_u32_e32 v59, vcc, 0, v121, vcc
	global_store_dwordx4 v[56:57], v[44:47], off offset:64 nt
	v_cvt_pk_bf16_f32 v28, v28, v29
	v_cvt_pk_bf16_f32 v29, v30, v31
	v_lshl_add_u64 v[44:45], v[120:121], 0, s[0:1]
	s_mov_b32 s0, 0x21c000
	v_add_co_u32_e32 v46, vcc, s0, v120
	v_cvt_pk_bf16_f32 v30, v24, v25
	v_cvt_pk_bf16_f32 v31, v26, v27
	s_mov_b64 s[0:1], 0x258000
	v_addc_co_u32_e32 v47, vcc, 0, v121, vcc
	global_store_dwordx4 v[44:45], v[28:31], off offset:64 nt
	v_cvt_pk_bf16_f32 v12, v12, v13
	v_cvt_pk_bf16_f32 v13, v14, v15
	v_lshl_add_u64 v[28:29], v[120:121], 0, s[0:1]
	s_mov_b32 s0, 0x258000
	v_add_co_u32_e32 v30, vcc, s0, v120
	v_cvt_pk_bf16_f32 v14, v8, v9
	v_cvt_pk_bf16_f32 v15, v10, v11
	s_mov_b64 s[0:1], 0x294000
	v_addc_co_u32_e32 v31, vcc, 0, v121, vcc
	global_store_dwordx4 v[28:29], v[12:15], off offset:64 nt
	v_cvt_pk_bf16_f32 v104, v116, v117
	v_cvt_pk_bf16_f32 v105, v118, v119
	v_lshl_add_u64 v[12:13], v[120:121], 0, s[0:1]
	s_mov_b32 s0, 0x294000
	v_add_co_u32_e32 v14, vcc, s0, v120
	v_cvt_pk_bf16_f32 v106, v112, v113
	v_cvt_pk_bf16_f32 v107, v114, v115
	v_cvt_pk_bf16_f32 v88, v100, v101
	v_cvt_pk_bf16_f32 v89, v102, v103
	v_cvt_pk_bf16_f32 v90, v96, v97
	v_cvt_pk_bf16_f32 v91, v98, v99
	v_cvt_pk_bf16_f32 v72, v84, v85
	v_cvt_pk_bf16_f32 v73, v86, v87
	v_cvt_pk_bf16_f32 v74, v80, v81
	v_cvt_pk_bf16_f32 v75, v82, v83
	v_cvt_pk_bf16_f32 v68, v68, v69
	v_cvt_pk_bf16_f32 v69, v70, v71
	v_cvt_pk_bf16_f32 v70, v64, v65
	v_cvt_pk_bf16_f32 v71, v66, v67
	v_cvt_pk_bf16_f32 v40, v52, v53
	v_cvt_pk_bf16_f32 v41, v54, v55
	v_cvt_pk_bf16_f32 v42, v48, v49
	v_cvt_pk_bf16_f32 v43, v50, v51
	v_cvt_pk_bf16_f32 v24, v36, v37
	v_cvt_pk_bf16_f32 v25, v38, v39
	v_cvt_pk_bf16_f32 v26, v32, v33
	v_cvt_pk_bf16_f32 v27, v34, v35
	v_cvt_pk_bf16_f32 v8, v20, v21
	v_cvt_pk_bf16_f32 v9, v22, v23
	v_cvt_pk_bf16_f32 v10, v16, v17
	v_cvt_pk_bf16_f32 v11, v18, v19
	v_addc_co_u32_e32 v15, vcc, 0, v121, vcc
	v_cvt_pk_bf16_f32 v4, v4, v5
	v_cvt_pk_bf16_f32 v5, v6, v7
	v_cvt_pk_bf16_f32 v6, v0, v1
	v_cvt_pk_bf16_f32 v7, v2, v3
	s_mov_b32 s6, s22
	s_mov_b32 s7, s30
	global_store_dwordx4 v[120:121], v[124:127], off nt
	global_store_dwordx4 v[110:111], v[104:107], off nt
	global_store_dwordx4 v[94:95], v[88:91], off nt
	global_store_dwordx4 v[78:79], v[72:75], off nt
	global_store_dwordx4 v[76:77], v[68:71], off offset:64 nt
	global_store_dwordx4 v[58:59], v[60:63], off nt
	global_store_dwordx4 v[46:47], v[40:43], off nt
	global_store_dwordx4 v[30:31], v[24:27], off nt
	global_store_dwordx4 v[14:15], v[8:11], off nt
	global_store_dwordx4 v[12:13], v[4:7], off offset:64 nt
	s_andn2_b64 vcc, exec, s[58:59]
	s_mov_b64 s[0:1], -1
	s_cbranch_vccnz .LBB0_622

.LBB0_1183:
	s_cmpk_lt_i32 s60, 0x80
	v_cmp_ne_u32_e32 vcc, 0, v144
	v_readlane_b32 s66, v252, 9
	s_cselect_b64 s[44:45], -1, 0
	s_and_b64 vcc, exec, vcc
	v_lshlrev_b32_e32 v176, 1, v136
	v_readlane_b32 s67, v252, 10
	v_readlane_b32 s64, v252, 13
	v_readlane_b32 s65, v252, 14
	s_cbranch_vccz .LBB0_1185
	s_lshl_b32 s0, s60, 8
	s_add_i32 s20, s60, 0x7fff80
	s_lshr_b32 s21, s60, 3
	s_and_b32 s22, s0, 0x700
	s_and_b64 s[0:1], s[44:45], exec
	s_cselect_b32 s0, s21, s20
	s_cselect_b32 s20, s22, 0x800
	s_lshl_b32 s1, s61, 8
	s_lshl_b32 s0, s0, 9
	s_add_i32 s0, s0, s1
	s_add_i32 s21, s0, 0xfffff400
	s_add_i32 s22, s0, 0xfffffc00
	v_readlane_b32 s0, v252, 32
	s_add_i32 s30, s21, s0
	s_add_i32 s0, s22, s0
	s_and_b32 s0, s0, 0xffffff80
	s_cmp_lt_i32 s61, 8
	s_cselect_b64 vcc, -1, 0
	v_or_b32_e32 v152, s0, v166
	s_and_b64 s[0:1], vcc, exec
	s_movk_i32 s0, 0x118
	s_cselect_b32 s0, s0, 0x120
	v_readlane_b32 s4, v253, 0
	v_readlane_b32 s5, v253, 1
	s_add_u32 s0, s4, s0
	s_addc_u32 s1, s5, 0
	s_load_dwordx2 s[0:1], s[0:1], 0x0
	v_or_b32_e32 v144, s30, v160
	v_cndmask_b32_e32 v144, v144, v152, vcc
	s_movk_i32 s4, 0x1200
	s_lshl_b32 s70, s20, 1
	s_waitcnt lgkmcnt(0)
	v_mov_b64_e32 v[148:149], s[0:1]
	v_mad_i64_i32 v[144:145], s[0:1], v144, s4, v[148:149]
	v_readlane_b32 s0, v252, 28
	v_lshl_add_u64 v[144:145], v[144:145], 0, s[70:71]
	s_lshl_b32 s42, s0, 1
	s_mov_b32 s43, s71
	v_lshl_add_u64 v[144:145], v[144:145], 0, s[42:43]
	v_lshl_add_u64 v[150:151], v[144:145], 0, v[176:177]
	v_cvt_pk_bf16_f32 v144, v124, v125
	v_cvt_pk_bf16_f32 v145, v126, v127
	v_cvt_pk_bf16_f32 v146, v120, v121
	v_cvt_pk_bf16_f32 v147, v122, v123
	global_store_dwordx4 v[150:151], v[144:147], off nt
	s_nop 1
	v_cvt_pk_bf16_f32 v144, v108, v109
	v_cvt_pk_bf16_f32 v145, v110, v111
	v_cvt_pk_bf16_f32 v146, v104, v105
	v_cvt_pk_bf16_f32 v147, v106, v107
	global_store_dwordx4 v[150:151], v[144:147], off offset:64 nt
	s_nop 1
	v_or_b32_e32 v144, 16, v152
	v_or_b32_e32 v145, s30, v163
	v_cndmask_b32_e32 v144, v145, v144, vcc
	v_mad_i64_i32 v[144:145], s[0:1], v144, s4, v[148:149]
	v_lshl_add_u64 v[144:145], v[144:145], 0, s[70:71]
	v_lshl_add_u64 v[144:145], v[144:145], 0, s[42:43]
	v_lshl_add_u64 v[150:151], v[144:145], 0, v[176:177]
	v_cvt_pk_bf16_f32 v144, v116, v117
	v_cvt_pk_bf16_f32 v145, v118, v119
	v_cvt_pk_bf16_f32 v146, v112, v113
	v_cvt_pk_bf16_f32 v147, v114, v115
	global_store_dwordx4 v[150:151], v[144:147], off nt
	s_nop 1
	v_cvt_pk_bf16_f32 v144, v92, v93
	v_cvt_pk_bf16_f32 v145, v94, v95
	v_cvt_pk_bf16_f32 v146, v88, v89
	v_cvt_pk_bf16_f32 v147, v90, v91
	global_store_dwordx4 v[150:151], v[144:147], off offset:64 nt
	s_nop 1
	v_or_b32_e32 v144, 32, v152
	v_or_b32_e32 v145, s30, v164
	v_cndmask_b32_e32 v144, v145, v144, vcc
	v_mad_i64_i32 v[144:145], s[0:1], v144, s4, v[148:149]
	v_lshl_add_u64 v[144:145], v[144:145], 0, s[70:71]
	v_lshl_add_u64 v[144:145], v[144:145], 0, s[42:43]
	v_lshl_add_u64 v[150:151], v[144:145], 0, v[176:177]
	v_cvt_pk_bf16_f32 v144, v100, v101
	v_cvt_pk_bf16_f32 v145, v102, v103
	v_cvt_pk_bf16_f32 v146, v96, v97
	v_cvt_pk_bf16_f32 v147, v98, v99
	global_store_dwordx4 v[150:151], v[144:147], off nt
	s_nop 1
	v_cvt_pk_bf16_f32 v144, v76, v77
	v_cvt_pk_bf16_f32 v145, v78, v79
	v_cvt_pk_bf16_f32 v146, v72, v73
	v_cvt_pk_bf16_f32 v147, v74, v75
	global_store_dwordx4 v[150:151], v[144:147], off offset:64 nt
	s_nop 1
	v_or_b32_e32 v144, 48, v152
	v_or_b32_e32 v145, s30, v165
	v_cndmask_b32_e32 v144, v145, v144, vcc
	v_mad_i64_i32 v[144:145], s[0:1], v144, s4, v[148:149]
	v_lshl_add_u64 v[144:145], v[144:145], 0, s[70:71]
	v_lshl_add_u64 v[144:145], v[144:145], 0, s[42:43]
	v_readlane_b32 s0, v252, 30
	v_lshl_add_u64 v[150:151], v[144:145], 0, v[176:177]
	v_cvt_pk_bf16_f32 v144, v84, v85
	v_cvt_pk_bf16_f32 v145, v86, v87
	v_cvt_pk_bf16_f32 v146, v80, v81
	v_cvt_pk_bf16_f32 v147, v82, v83
	s_add_i32 s22, s22, s0
	global_store_dwordx4 v[150:151], v[144:147], off nt
	s_add_i32 s21, s21, s0
	s_and_b32 s0, s22, 0xffffff80
	v_cvt_pk_bf16_f32 v144, v68, v69
	v_cvt_pk_bf16_f32 v145, v70, v71
	v_cvt_pk_bf16_f32 v146, v64, v65
	v_cvt_pk_bf16_f32 v147, v66, v67
	global_store_dwordx4 v[150:151], v[144:147], off offset:64 nt
	v_or_b32_e32 v152, s0, v167
	s_nop 0
	v_or_b32_e32 v144, s21, v160
	v_cndmask_b32_e32 v144, v144, v152, vcc
	v_mad_i64_i32 v[144:145], s[0:1], v144, s4, v[148:149]
	v_lshl_add_u64 v[144:145], v[144:145], 0, s[70:71]
	v_lshl_add_u64 v[144:145], v[144:145], 0, s[42:43]
	v_lshl_add_u64 v[150:151], v[144:145], 0, v[176:177]
	v_cvt_pk_bf16_f32 v144, v60, v61
	v_cvt_pk_bf16_f32 v145, v62, v63
	v_cvt_pk_bf16_f32 v146, v56, v57
	v_cvt_pk_bf16_f32 v147, v58, v59
	global_store_dwordx4 v[150:151], v[144:147], off nt
	s_nop 1
	v_cvt_pk_bf16_f32 v144, v44, v45
	v_cvt_pk_bf16_f32 v145, v46, v47
	v_cvt_pk_bf16_f32 v146, v40, v41
	v_cvt_pk_bf16_f32 v147, v42, v43
	global_store_dwordx4 v[150:151], v[144:147], off offset:64 nt
	s_nop 1
	v_or_b32_e32 v144, 16, v152
	v_or_b32_e32 v145, s21, v163
	v_cndmask_b32_e32 v144, v145, v144, vcc
	v_mad_i64_i32 v[144:145], s[0:1], v144, s4, v[148:149]
	v_lshl_add_u64 v[144:145], v[144:145], 0, s[70:71]
	v_lshl_add_u64 v[144:145], v[144:145], 0, s[42:43]
	v_lshl_add_u64 v[150:151], v[144:145], 0, v[176:177]
	v_cvt_pk_bf16_f32 v144, v52, v53
	v_cvt_pk_bf16_f32 v145, v54, v55
	v_cvt_pk_bf16_f32 v146, v48, v49
	v_cvt_pk_bf16_f32 v147, v50, v51
	global_store_dwordx4 v[150:151], v[144:147], off nt
	s_nop 1
	v_cvt_pk_bf16_f32 v144, v28, v29
	v_cvt_pk_bf16_f32 v145, v30, v31
	v_cvt_pk_bf16_f32 v146, v24, v25
	v_cvt_pk_bf16_f32 v147, v26, v27
	global_store_dwordx4 v[150:151], v[144:147], off offset:64 nt
	s_nop 1
	v_or_b32_e32 v144, 32, v152
	v_or_b32_e32 v145, s21, v164
	v_cndmask_b32_e32 v144, v145, v144, vcc
	v_mad_i64_i32 v[144:145], s[0:1], v144, s4, v[148:149]
	v_lshl_add_u64 v[144:145], v[144:145], 0, s[70:71]
	v_lshl_add_u64 v[144:145], v[144:145], 0, s[42:43]
	v_lshl_add_u64 v[150:151], v[144:145], 0, v[176:177]
	v_cvt_pk_bf16_f32 v144, v36, v37
	v_cvt_pk_bf16_f32 v145, v38, v39
	v_cvt_pk_bf16_f32 v146, v32, v33
	v_cvt_pk_bf16_f32 v147, v34, v35
	global_store_dwordx4 v[150:151], v[144:147], off nt
	s_nop 1
	v_cvt_pk_bf16_f32 v144, v12, v13
	v_cvt_pk_bf16_f32 v145, v14, v15
	v_cvt_pk_bf16_f32 v146, v8, v9
	v_cvt_pk_bf16_f32 v147, v10, v11
	global_store_dwordx4 v[150:151], v[144:147], off offset:64 nt
	s_nop 1
	v_or_b32_e32 v144, 48, v152
	v_or_b32_e32 v145, s21, v165
	v_cndmask_b32_e32 v144, v145, v144, vcc
	v_mad_i64_i32 v[144:145], s[0:1], v144, s4, v[148:149]
	v_lshl_add_u64 v[144:145], v[144:145], 0, s[70:71]
	v_lshl_add_u64 v[144:145], v[144:145], 0, s[42:43]
	v_lshl_add_u64 v[148:149], v[144:145], 0, v[176:177]
	v_cvt_pk_bf16_f32 v144, v20, v21
	v_cvt_pk_bf16_f32 v145, v22, v23
	v_cvt_pk_bf16_f32 v146, v16, v17
	v_cvt_pk_bf16_f32 v147, v18, v19
	global_store_dwordx4 v[148:149], v[144:147], off nt
	s_mov_b64 s[0:1], 0
	s_nop 0
	v_cvt_pk_bf16_f32 v144, v4, v5
	v_cvt_pk_bf16_f32 v145, v6, v7
	v_cvt_pk_bf16_f32 v146, v0, v1
	v_cvt_pk_bf16_f32 v147, v2, v3
	global_store_dwordx4 v[148:149], v[144:147], off offset:64 nt
	s_branch .LBB0_1186

.LBB0_1204:
	s_lshl_b32 s20, s61, 8
	s_cmp_lt_u32 s61, 12
	s_movk_i32 s0, 0xfe00
	s_cselect_b32 s21, s0, 0xfffffc00
	s_and_b64 s[0:1], s[62:63], exec
	s_cselect_b32 s0, 0, s21
	s_ashr_i32 s61, s60, 31
	s_add_i32 s0, s0, s20
	s_lshl_b64 s[20:21], s[60:61], 8
	v_lshl_add_u64 v[144:145], v[138:139], 0, s[20:21]
	v_readlane_b32 s20, v253, 0
	v_readlane_b32 s21, v253, 1
	s_mov_b32 s30, s7
	s_mov_b32 s22, s6
	s_load_dwordx16 s[4:19], s[20:21], 0xf0
	v_cvt_pk_bf16_f32 v124, v124, v125
	v_cvt_pk_bf16_f32 v125, v126, v127
	v_cvt_pk_bf16_f32 v126, v120, v121
	s_waitcnt lgkmcnt(0)
	s_movk_i32 s4, 0x3c00
	v_mov_b64_e32 v[120:121], s[12:13]
	v_mad_u64_u32 v[120:121], s[20:21], v144, s4, v[120:121]
	v_cvt_pk_bf16_f32 v127, v122, v123
	v_mov_b32_e32 v122, v121
	v_mad_u64_u32 v[122:123], s[20:21], v145, s4, v[122:123]
	s_ashr_i32 s1, s0, 31
	v_mov_b32_e32 v121, v122
	v_lshl_add_u64 v[120:121], s[0:1], 1, v[120:121]
	v_readlane_b32 s0, v252, 28
	s_lshl_b32 s70, s0, 1
	v_lshl_add_u64 v[120:121], v[120:121], 0, s[70:71]
	v_lshl_add_u64 v[120:121], v[120:121], 0, v[176:177]
	v_cvt_pk_bf16_f32 v108, v108, v109
	v_cvt_pk_bf16_f32 v109, v110, v111
	v_cvt_pk_bf16_f32 v110, v104, v105
	v_cvt_pk_bf16_f32 v111, v106, v107
	s_mov_b64 s[0:1], 0x3c000
	global_store_dwordx4 v[120:121], v[108:111], off offset:64 nt
	v_cvt_pk_bf16_f32 v92, v92, v93
	v_cvt_pk_bf16_f32 v93, v94, v95
	v_lshl_add_u64 v[108:109], v[120:121], 0, s[0:1]
	s_mov_b32 s0, 0x3c000
	v_add_co_u32_e32 v110, vcc, s0, v120
	v_cvt_pk_bf16_f32 v94, v88, v89
	v_cvt_pk_bf16_f32 v95, v90, v91
	s_mov_b64 s[0:1], 0x78000
	v_addc_co_u32_e32 v111, vcc, 0, v121, vcc
	global_store_dwordx4 v[108:109], v[92:95], off offset:64 nt
	v_cvt_pk_bf16_f32 v76, v76, v77
	v_cvt_pk_bf16_f32 v77, v78, v79
	v_lshl_add_u64 v[92:93], v[120:121], 0, s[0:1]
	s_mov_b32 s0, 0x78000
	v_add_co_u32_e32 v94, vcc, s0, v120
	v_cvt_pk_bf16_f32 v78, v72, v73
	v_cvt_pk_bf16_f32 v79, v74, v75
	s_mov_b64 s[0:1], 0xb4000
	v_addc_co_u32_e32 v95, vcc, 0, v121, vcc
	global_store_dwordx4 v[92:93], v[76:79], off offset:64 nt
	v_cvt_pk_bf16_f32 v60, v60, v61
	v_cvt_pk_bf16_f32 v61, v62, v63
	v_lshl_add_u64 v[76:77], v[120:121], 0, s[0:1]
	s_mov_b32 s0, 0xb4000
	v_add_co_u32_e32 v78, vcc, s0, v120
	s_mov_b64 s[0:1], 0x1e0000
	s_nop 0
	v_addc_co_u32_e32 v79, vcc, 0, v121, vcc
	v_cvt_pk_bf16_f32 v62, v56, v57
	v_lshl_add_u64 v[56:57], v[120:121], 0, s[0:1]
	s_mov_b32 s0, 0x1e0000
	v_cvt_pk_bf16_f32 v63, v58, v59
	v_add_co_u32_e32 v58, vcc, s0, v120
	v_cvt_pk_bf16_f32 v44, v44, v45
	v_cvt_pk_bf16_f32 v45, v46, v47
	v_cvt_pk_bf16_f32 v46, v40, v41
	v_cvt_pk_bf16_f32 v47, v42, v43
	s_mov_b64 s[0:1], 0x21c000
	v_addc_co_u32_e32 v59, vcc, 0, v121, vcc
	global_store_dwordx4 v[56:57], v[44:47], off offset:64 nt
	v_cvt_pk_bf16_f32 v28, v28, v29
	v_cvt_pk_bf16_f32 v29, v30, v31
	v_lshl_add_u64 v[44:45], v[120:121], 0, s[0:1]
	s_mov_b32 s0, 0x21c000
	v_add_co_u32_e32 v46, vcc, s0, v120
	v_cvt_pk_bf16_f32 v30, v24, v25
	v_cvt_pk_bf16_f32 v31, v26, v27
	s_mov_b64 s[0:1], 0x258000
	v_addc_co_u32_e32 v47, vcc, 0, v121, vcc
	global_store_dwordx4 v[44:45], v[28:31], off offset:64 nt
	v_cvt_pk_bf16_f32 v12, v12, v13
	v_cvt_pk_bf16_f32 v13, v14, v15
	v_lshl_add_u64 v[28:29], v[120:121], 0, s[0:1]
	s_mov_b32 s0, 0x258000
	v_add_co_u32_e32 v30, vcc, s0, v120
	v_cvt_pk_bf16_f32 v14, v8, v9
	v_cvt_pk_bf16_f32 v15, v10, v11
	s_mov_b64 s[0:1], 0x294000
	v_addc_co_u32_e32 v31, vcc, 0, v121, vcc
	global_store_dwordx4 v[28:29], v[12:15], off offset:64 nt
	v_cvt_pk_bf16_f32 v104, v116, v117
	v_cvt_pk_bf16_f32 v105, v118, v119
	v_lshl_add_u64 v[12:13], v[120:121], 0, s[0:1]
	s_mov_b32 s0, 0x294000
	v_add_co_u32_e32 v14, vcc, s0, v120
	v_cvt_pk_bf16_f32 v106, v112, v113
	v_cvt_pk_bf16_f32 v107, v114, v115
	v_cvt_pk_bf16_f32 v88, v100, v101
	v_cvt_pk_bf16_f32 v89, v102, v103
	v_cvt_pk_bf16_f32 v90, v96, v97
	v_cvt_pk_bf16_f32 v91, v98, v99
	v_cvt_pk_bf16_f32 v72, v84, v85
	v_cvt_pk_bf16_f32 v73, v86, v87
	v_cvt_pk_bf16_f32 v74, v80, v81
	v_cvt_pk_bf16_f32 v75, v82, v83
	v_cvt_pk_bf16_f32 v68, v68, v69
	v_cvt_pk_bf16_f32 v69, v70, v71
	v_cvt_pk_bf16_f32 v70, v64, v65
	v_cvt_pk_bf16_f32 v71, v66, v67
	v_cvt_pk_bf16_f32 v40, v52, v53
	v_cvt_pk_bf16_f32 v41, v54, v55
	v_cvt_pk_bf16_f32 v42, v48, v49
	v_cvt_pk_bf16_f32 v43, v50, v51
	v_cvt_pk_bf16_f32 v24, v36, v37
	v_cvt_pk_bf16_f32 v25, v38, v39
	v_cvt_pk_bf16_f32 v26, v32, v33
	v_cvt_pk_bf16_f32 v27, v34, v35
	v_cvt_pk_bf16_f32 v8, v20, v21
	v_cvt_pk_bf16_f32 v9, v22, v23
	v_cvt_pk_bf16_f32 v10, v16, v17
	v_cvt_pk_bf16_f32 v11, v18, v19
	v_addc_co_u32_e32 v15, vcc, 0, v121, vcc
	v_cvt_pk_bf16_f32 v4, v4, v5
	v_cvt_pk_bf16_f32 v5, v6, v7
	v_cvt_pk_bf16_f32 v6, v0, v1
	v_cvt_pk_bf16_f32 v7, v2, v3
	s_mov_b32 s6, s22
	s_mov_b32 s7, s30
	global_store_dwordx4 v[120:121], v[124:127], off nt
	global_store_dwordx4 v[110:111], v[104:107], off nt
	global_store_dwordx4 v[94:95], v[88:91], off nt
	global_store_dwordx4 v[78:79], v[72:75], off nt
	global_store_dwordx4 v[76:77], v[68:71], off offset:64 nt
	global_store_dwordx4 v[58:59], v[60:63], off nt
	global_store_dwordx4 v[46:47], v[40:43], off nt
	global_store_dwordx4 v[30:31], v[24:27], off nt
	global_store_dwordx4 v[14:15], v[8:11], off nt
	global_store_dwordx4 v[12:13], v[4:7], off offset:64 nt
